# grid barrier: followers poll the top-level counter directly (per-XCD release word dropped)
# baseline (speedup 1.0000x reference)
.Lxbn0_p2_ok:
	buffer_inv sc1
	s_branch .Lxbn0_end
.Lxbn0_fol:
	s_add_u32 s28, s18, 0x3400
	s_addc_u32 s29, s19, 0
	s_mul_i32 s21, s98, s100
	s_mov_b32 s22, 0
